# compact index-key copy + DSA collect fast path combined
# baseline (speedup 1.0000x reference)
; __device__ __forceinline__ void dsa_item(const KP& p, int b, int tile, char* smem) {
;     ...
;     for (int kt = wid; kt < nkt; kt += 4) {
;       h8 ca[2];
; #pragma unroll
;       for (int i = 0; i < 2; ++i) ca[i] = na[i];
;       loadk(kt + 4 < nkt ? kt + 4 : kt, na);
;       float sc[8];
;       scores(ca, sc);
.LBB0_1081:
	s_waitcnt vmcnt(0)
	v_mov_b64_e32 v[88:89], v[48:49]
	v_mov_b64_e32 v[86:87], v[46:47]
	v_mfma_f32_16x16x32_f16 v[54:57], v[50:53], v[38:41], 0
	v_mov_b32_e32 v0, v162
	v_add_u32_e32 v162, 4, v0
	v_cmp_gt_i32_e32 vcc, s68, v162
	v_mfma_f32_16x16x32_f16 v[46:49], v[86:89], v[38:41], 0
	v_mov_b32_e32 v127, v1
	v_cndmask_b32_e32 v0, v0, v162, vcc
	v_lshl_or_b32 v0, v0, 5, v157
	v_mfma_f32_16x16x32_f16 v[90:93], v[50:53], v[34:37], v[54:57]
	v_cmp_le_i32_e64 s[60:61], v160, v133
	v_mfma_f32_16x16x32_f16 v[54:57], v[86:89], v[34:37], v[46:49]
	s_nop 2
	v_mov_b64_e32 v[46:47], s[78:79]
	v_mad_i64_i32 v[48:49], s[2:3], v0, s5, v[46:47]
	v_lshl_add_u64 v[48:49], v[48:49], 0, v[126:127]
	v_or_b32_e32 v0, 16, v0
	v_add_co_u32_e32 v48, vcc, s23, v48
	v_mad_i64_i32 v[46:47], s[2:3], v0, s5, v[46:47]
	s_nop 0
	v_addc_co_u32_e32 v49, vcc, 0, v49, vcc
	v_lshl_add_u64 v[46:47], v[46:47], 0, v[126:127]
	v_add_co_u32_e32 v46, vcc, s23, v46
	v_mfma_f32_16x16x32_f16 v[94:97], v[50:53], v[26:29], 0
	s_nop 0
	v_addc_co_u32_e32 v47, vcc, 0, v47, vcc
	v_cmp_le_i32_e32 vcc, s68, v162
	v_mfma_f32_16x16x32_f16 v[98:101], v[50:53], v[2:5], 0
	v_mfma_f32_16x16x32_f16 v[102:105], v[50:53], v[6:9], 0
	v_mfma_f32_16x16x32_f16 v[106:109], v[50:53], v[10:13], 0
	v_mfma_f32_16x16x32_f16 v[110:113], v[50:53], v[14:17], 0
	v_mfma_f32_16x16x32_f16 v[114:117], v[50:53], v[18:21], 0
	v_mfma_f32_16x16x32_f16 v[118:121], v[50:53], v[22:25], 0
	v_mfma_f32_16x16x32_f16 v[122:125], v[50:53], v[30:33], 0
	v_readlane_b32 s2, v251, 20
	v_readlane_b32 s3, v251, 21
	v_add_lshl_u32 v48, v126, v157, 4
	v_lshl_add_u32 v48, v162, 11, v48
	s_nop 4
	global_load_dwordx4 v[50:53], v48, s[2:3]
	global_load_dwordx4 v[46:49], v48, s[2:3] offset:1024
	v_mfma_f32_16x16x32_f16 v[58:61], v[86:89], v[26:29], 0
	v_mfma_f32_16x16x32_f16 v[62:65], v[86:89], v[2:5], 0
	v_mfma_f32_16x16x32_f16 v[66:69], v[86:89], v[6:9], 0
	v_mfma_f32_16x16x32_f16 v[70:73], v[86:89], v[10:13], 0
	v_mfma_f32_16x16x32_f16 v[74:77], v[86:89], v[14:17], 0
	v_mfma_f32_16x16x32_f16 v[78:81], v[86:89], v[18:21], 0
	v_mfma_f32_16x16x32_f16 v[82:85], v[86:89], v[22:25], 0
	v_mfma_f32_16x16x32_f16 v[86:89], v[86:89], v[30:33], 0
	s_xor_b64 s[14:15], s[46:47], exec
	s_cmp_lg_u64 s[14:15], 0
	s_cbranch_scc1 .Lcf_slow
; __device__ __forceinline__ void dsa_item(const KP& p, int b, int tile, char* smem) {
;     ...
; #pragma unroll
;       for (int q = 0; q < 8; ++q) {
;         const int key = kt * 32 + (q >> 2) * 16 + 4 * hq + (q & 3);
;         if (key <= myt) {
;           const uint32_t u32 = skey(sc[q]);
;           bool take, isc = false;
;           if (st0 == 0) take = (((unsigned long long)u32 << 16) | (unsigned long long)(8191 - key)) >= mytk;
;           else {
;             const uint32_t p16 = u32 >> 16;
;             take = p16 > (uint32_t)myp16;
;             isc = p16 == (uint32_t)myp16;
;           }
;           if (take) {
;             const int pos = atomicAdd(&cnt[mytok], 1);
;             if (pos < 256) sel[mytok * 256 + pos] = (unsigned short)key;
;           } else if (isc) {
;             const int pos = atomicAdd(&ccnt[mytok], 1);
;             if (pos < DSA_CAP) cand[mytok * 128 + pos] = ((unsigned long long)u32 << 16) | (unsigned long long)(8191 - key);
;           }
;         }
	s_mov_b64 s[2:3], exec
	s_and_b64 s[14:15], exec, vcc
	s_or_b64 s[96:97], s[14:15], s[96:97]
	v_sub_u32_e32 v166, v133, v160
	v_fma_f32 v194, |v94|, v128, v90
	v_fma_f32 v195, |v95|, v128, v91
	v_fma_f32 v196, |v96|, v128, v92
	v_fma_f32 v197, |v97|, v128, v93
	v_fma_f32 v194, |v98|, v130, v194
	v_fma_f32 v195, |v99|, v130, v195
	v_fma_f32 v196, |v100|, v130, v196
	v_fma_f32 v197, |v101|, v130, v197
	v_fma_f32 v194, |v102|, v132, v194
	v_fma_f32 v195, |v103|, v132, v195
	v_fma_f32 v196, |v104|, v132, v196
	v_fma_f32 v197, |v105|, v132, v197
	v_fma_f32 v194, |v106|, v134, v194
	v_fma_f32 v195, |v107|, v134, v195
	v_fma_f32 v196, |v108|, v134, v196
	v_fma_f32 v197, |v109|, v134, v197
	v_fma_f32 v194, |v110|, v136, v194
	v_fma_f32 v195, |v111|, v136, v195
	v_fma_f32 v196, |v112|, v136, v196
	v_fma_f32 v197, |v113|, v136, v197
	v_fma_f32 v194, |v114|, v138, v194
	v_fma_f32 v195, |v115|, v138, v195
	v_fma_f32 v196, |v116|, v138, v196
	v_fma_f32 v197, |v117|, v138, v197
	v_fma_f32 v194, |v118|, v140, v194
	v_fma_f32 v195, |v119|, v140, v195
	v_fma_f32 v196, |v120|, v140, v196
	v_fma_f32 v197, |v121|, v140, v197
	v_fma_f32 v194, |v122|, v142, v194
	v_fma_f32 v195, |v123|, v142, v195
	v_fma_f32 v196, |v124|, v142, v196
	v_fma_f32 v197, |v125|, v142, v197
	v_add_f32_e32 v194, 0, v194
	v_add_f32_e32 v195, 0, v195
	v_add_f32_e32 v196, 0, v196
	v_add_f32_e32 v197, 0, v197
	v_ashrrev_i32_e32 v198, 31, v194
	v_ashrrev_i32_e32 v199, 31, v195
	v_ashrrev_i32_e32 v200, 31, v196
	v_ashrrev_i32_e32 v201, 31, v197
	v_or_b32_e32 v198, 0x80000000, v198
	v_or_b32_e32 v199, 0x80000000, v199
	v_or_b32_e32 v200, 0x80000000, v200
	v_or_b32_e32 v201, 0x80000000, v201
	v_xor_b32_e32 v202, v194, v198
	v_xor_b32_e32 v203, v195, v199
	v_xor_b32_e32 v204, v196, v200
	v_xor_b32_e32 v205, v197, v201
	v_cmp_ge_i32_e64 s[60:61], v166, 0
	v_cmp_gt_u32_sdwa s[30:31], v202, v42 src0_sel:WORD_1 src1_sel:DWORD
	v_cmp_eq_u32_sdwa s[66:67], v202, v42 src0_sel:WORD_1 src1_sel:DWORD
	s_and_b64 s[30:31], s[30:31], s[60:61]
	s_and_b64 s[66:67], s[66:67], s[60:61]
	v_cndmask_b32_e64 v206, 0, 1, s[30:31]
	v_cndmask_b32_e64 v210, 0, 1, s[66:67]
	v_cmp_ge_i32_e64 s[60:61], v166, 1
	v_cmp_gt_u32_sdwa s[30:31], v203, v42 src0_sel:WORD_1 src1_sel:DWORD
	v_cmp_eq_u32_sdwa s[66:67], v203, v42 src0_sel:WORD_1 src1_sel:DWORD
	s_and_b64 s[30:31], s[30:31], s[60:61]
	s_and_b64 s[66:67], s[66:67], s[60:61]
	v_cndmask_b32_e64 v207, 0, 1, s[30:31]
	v_cndmask_b32_e64 v211, 0, 1, s[66:67]
	v_cmp_ge_i32_e64 s[60:61], v166, 2
	v_cmp_gt_u32_sdwa s[30:31], v204, v42 src0_sel:WORD_1 src1_sel:DWORD
	v_cmp_eq_u32_sdwa s[66:67], v204, v42 src0_sel:WORD_1 src1_sel:DWORD
	s_and_b64 s[30:31], s[30:31], s[60:61]
	s_and_b64 s[66:67], s[66:67], s[60:61]
	v_cndmask_b32_e64 v208, 0, 1, s[30:31]
	v_cndmask_b32_e64 v212, 0, 1, s[66:67]
	v_cmp_ge_i32_e64 s[60:61], v166, 3
	v_cmp_gt_u32_sdwa s[30:31], v205, v42 src0_sel:WORD_1 src1_sel:DWORD
	v_cmp_eq_u32_sdwa s[66:67], v205, v42 src0_sel:WORD_1 src1_sel:DWORD
	s_and_b64 s[30:31], s[30:31], s[60:61]
	s_and_b64 s[66:67], s[66:67], s[60:61]
	v_cndmask_b32_e64 v209, 0, 1, s[30:31]
	v_cndmask_b32_e64 v213, 0, 1, s[66:67]
	v_cmp_ne_u32_e32 vcc, 0, v206
	s_mov_b64 exec, vcc
	ds_add_rtn_u32 v214, v145, v206 offset:41344
	s_mov_b64 exec, s[2:3]
	v_cmp_ne_u32_e32 vcc, 0, v207
	s_mov_b64 exec, vcc
	ds_add_rtn_u32 v215, v145, v207 offset:41344
	s_mov_b64 exec, s[2:3]
	v_cmp_ne_u32_e32 vcc, 0, v208
	s_mov_b64 exec, vcc
	ds_add_rtn_u32 v216, v145, v208 offset:41344
	s_mov_b64 exec, s[2:3]
	v_cmp_ne_u32_e32 vcc, 0, v209
	s_mov_b64 exec, vcc
	ds_add_rtn_u32 v217, v145, v209 offset:41344
	s_mov_b64 exec, s[2:3]
	v_cmp_ne_u32_e32 vcc, 0, v210
	s_mov_b64 exec, vcc
	ds_add_rtn_u32 v218, v145, v210 offset:41408
	s_mov_b64 exec, s[2:3]
	v_cmp_ne_u32_e32 vcc, 0, v211
	s_mov_b64 exec, vcc
	ds_add_rtn_u32 v219, v145, v211 offset:41408
	s_mov_b64 exec, s[2:3]
	v_cmp_ne_u32_e32 vcc, 0, v212
	s_mov_b64 exec, vcc
	ds_add_rtn_u32 v220, v145, v212 offset:41408
	s_mov_b64 exec, s[2:3]
	v_cmp_ne_u32_e32 vcc, 0, v213
	s_mov_b64 exec, vcc
	ds_add_rtn_u32 v221, v145, v213 offset:41408
	s_mov_b64 exec, s[2:3]
	v_lshlrev_b32_e32 v198, 8, v206
	v_lshlrev_b32_e32 v199, 8, v207
	v_lshlrev_b32_e32 v200, 8, v208
	v_lshlrev_b32_e32 v201, 8, v209
	v_lshlrev_b32_e32 v194, 7, v210
	v_lshlrev_b32_e32 v195, 7, v211
	v_lshlrev_b32_e32 v196, 7, v212
	v_lshlrev_b32_e32 v197, 7, v213
	s_waitcnt lgkmcnt(0)
	v_cmp_lt_u32_e32 vcc, v214, v198
	v_lshl_add_u32 v167, v214, 1, v43
	s_mov_b64 exec, vcc
	ds_write_b16 v167, v160 offset:32768
	s_mov_b64 exec, s[2:3]
	v_cmp_lt_u32_e32 vcc, v215, v199
	v_lshl_add_u32 v167, v215, 1, v43
	v_add_u32_e32 v168, 1, v160
	s_mov_b64 exec, vcc
	ds_write_b16 v167, v168 offset:32768
	s_mov_b64 exec, s[2:3]
	v_cmp_lt_u32_e32 vcc, v216, v200
	v_lshl_add_u32 v167, v216, 1, v43
	v_add_u32_e32 v168, 2, v160
	s_mov_b64 exec, vcc
	ds_write_b16 v167, v168 offset:32768
	s_mov_b64 exec, s[2:3]
	v_cmp_lt_u32_e32 vcc, v217, v201
	v_lshl_add_u32 v167, v217, 1, v43
	v_add_u32_e32 v168, 3, v160
	s_mov_b64 exec, vcc
	ds_write_b16 v167, v168 offset:32768
	s_mov_b64 exec, s[2:3]
	v_cmp_lt_u32_e32 vcc, v218, v194
	s_mov_b64 exec, vcc
	s_cbranch_execz .Lcf_nc00
	v_lshrrev_b32_e32 v223, 16, v202
	v_mov_b32_e32 v169, v161
	v_lshl_or_b32 v222, v202, 16, v169
	v_lshl_add_u32 v167, v218, 3, v147
	ds_write_b64 v167, v[222:223] offset:16384
